# combo7: combo6 plus the barrier's cache invalidate issued while waiting (before polling) instead of after the release is observed
# speedup vs baseline: 1.0244x; 1.0078x over previous
; __device__ __forceinline__ unsigned xb_ld(unsigned* p)              { return __hip_atomic_load(p, __ATOMIC_RELAXED, __HIP_MEMORY_SCOPE_AGENT); }
; __device__ __forceinline__ unsigned xb_add(unsigned* p, unsigned v) { return __hip_atomic_fetch_add(p, v, __ATOMIC_RELAXED, __HIP_MEMORY_SCOPE_AGENT); }
; #define XB_SPIN(cond, bar) do { unsigned _sp = 0; while (cond) { __builtin_amdgcn_s_sleep(1); \
;     if ((++_sp & 255u) == 0u) { if (xb_ld(&(bar)[XB_TMO])) break; if (_sp > XB_SPIN_CAP) { atomicAdd(&(bar)[XB_TMO], 1u); break; } } } } while (0)
; __device__ __forceinline__ void xcd_barrier(const XcdBarrier& b) {
;     ...
;         const unsigned old = xb_add(&bar[XB_XSUB(b.x)], 1u);
;         const unsigned gen = old / nloc;
;         if (old + 1u == (gen + 1u) * nloc) {
;             __builtin_amdgcn_fence(__ATOMIC_RELEASE, "agent");
;             asm volatile("s_waitcnt vmcnt(0)" ::: "memory");
;             const unsigned og = xb_add(&bar[XB_TOP], 1u);
;             const unsigned tg = og / nx;
;             if (og + 1u == (tg + 1u) * nx) xb_add(&bar[XB_TOPGEN], 1u);
;             else XB_SPIN(xb_ld(&bar[XB_TOPGEN]) == tg, bar);
;             __builtin_amdgcn_fence(__ATOMIC_ACQUIRE, "agent");
;             xb_add(&bar[XB_XGEN(b.x)], 1u);
;             asm volatile("s_waitcnt vmcnt(0)" ::: "memory");
;         } else {
;             XB_SPIN(xb_ld(&bar[XB_XGEN(b.x)]) == gen, bar);
;             __builtin_amdgcn_fence(__ATOMIC_ACQUIRE, "agent");
;             asm volatile("s_waitcnt vmcnt(0)" ::: "memory");
.LBB0_92:
	s_or_b64 exec, exec, s[6:7]
	v_cvt_f32_u32_e32 v4, v2
	s_waitcnt vmcnt(0)
	v_readfirstlane_b32 s4, v3
	v_sub_u32_e32 v3, 0, v2
	v_rcp_iflag_f32_e32 v4, v4
	v_add_u32_e32 v5, s4, v1
	v_mul_f32_e32 v4, 0x4f7ffffe, v4
	v_cvt_u32_f32_e32 v4, v4
	v_mul_lo_u32 v1, v3, v4
	v_mul_hi_u32 v1, v4, v1
	v_add_u32_e32 v1, v4, v1
	v_mul_hi_u32 v1, v5, v1
	v_mul_lo_u32 v3, v1, v2
	v_sub_u32_e32 v3, v5, v3
	v_add_u32_e32 v4, 1, v1
	v_cmp_ge_u32_e32 vcc, v3, v2
	s_nop 1
	v_cndmask_b32_e32 v1, v1, v4, vcc
	v_sub_u32_e32 v4, v3, v2
	v_cndmask_b32_e32 v3, v3, v4, vcc
	v_add_u32_e32 v4, 1, v1
	v_cmp_ge_u32_e32 vcc, v3, v2
	v_add_u32_e32 v3, 1, v5
	s_nop 0
	v_cndmask_b32_e32 v1, v1, v4, vcc
	v_mul_lo_u32 v4, v2, v1
	v_add_u32_e32 v2, v4, v2
	v_cmp_ne_u32_e32 vcc, v3, v2
	s_and_saveexec_b64 s[4:5], vcc
	s_xor_b64 s[4:5], exec, s[4:5]
	s_cbranch_execz .LBB0_106
	s_waitcnt lgkmcnt(0)
	buffer_inv sc1
	v_mov_b32_e32 v0, 0
	s_add_u32 s10, s68, 0xd6b0500
	s_addc_u32 s11, s69, 0
	s_nop 0
	global_load_dword v0, v0, s[10:11] sc1
	s_waitcnt vmcnt(0)
	v_cmp_eq_u32_e32 vcc, v0, v1
	s_and_saveexec_b64 s[6:7], vcc
	s_cbranch_execz .LBB0_105
	s_add_u32 s8, s68, 0xd6ad200
	s_addc_u32 s9, s69, 0
	s_mov_b32 s22, 1
	s_mov_b64 s[12:13], 0
	v_mov_b32_e32 v0, 0
	s_branch .LBB0_96

; __device__ __forceinline__ unsigned xb_ld(unsigned* p)              { return __hip_atomic_load(p, __ATOMIC_RELAXED, __HIP_MEMORY_SCOPE_AGENT); }
; __device__ __forceinline__ unsigned xb_add(unsigned* p, unsigned v) { return __hip_atomic_fetch_add(p, v, __ATOMIC_RELAXED, __HIP_MEMORY_SCOPE_AGENT); }
; #define XB_SPIN(cond, bar) do { unsigned _sp = 0; while (cond) { __builtin_amdgcn_s_sleep(1); \
;     if ((++_sp & 255u) == 0u) { if (xb_ld(&(bar)[XB_TMO])) break; if (_sp > XB_SPIN_CAP) { atomicAdd(&(bar)[XB_TMO], 1u); break; } } } } while (0)
; __device__ __forceinline__ void xcd_barrier(const XcdBarrier& b) {
;     ...
;             __builtin_amdgcn_fence(__ATOMIC_RELEASE, "agent");
;             asm volatile("s_waitcnt vmcnt(0)" ::: "memory");
;             const unsigned og = xb_add(&bar[XB_TOP], 1u);
;             const unsigned tg = og / nx;
;             if (og + 1u == (tg + 1u) * nx) xb_add(&bar[XB_TOPGEN], 1u);
;             else XB_SPIN(xb_ld(&bar[XB_TOPGEN]) == tg, bar);
;             __builtin_amdgcn_fence(__ATOMIC_ACQUIRE, "agent");
;             xb_add(&bar[XB_XGEN(b.x)], 1u);
;             asm volatile("s_waitcnt vmcnt(0)" ::: "memory");
;         } else {
;             XB_SPIN(xb_ld(&bar[XB_XGEN(b.x)]) == gen, bar);
;             __builtin_amdgcn_fence(__ATOMIC_ACQUIRE, "agent");
;             asm volatile("s_waitcnt vmcnt(0)" ::: "memory");
.LBB0_105:
	s_or_b64 exec, exec, s[6:7]
	s_waitcnt vmcnt(0)
	s_waitcnt vmcnt(0)
.LBB0_106:
	s_andn2_saveexec_b64 s[4:5], s[4:5]
	s_cbranch_execz .LBB0_126
	s_mov_b64 s[4:5], exec
	buffer_wbl2 sc1
	s_waitcnt lgkmcnt(0)
	s_waitcnt vmcnt(0)
	buffer_inv sc1
	v_mbcnt_lo_u32_b32 v1, s4, 0
	v_mbcnt_hi_u32_b32 v1, s5, v1
	v_cmp_eq_u32_e32 vcc, 0, v1
	s_and_saveexec_b64 s[6:7], vcc
	s_cbranch_execz .LBB0_109
	s_bcnt1_i32_b64 s4, s[4:5]
	v_mov_b32_e32 v2, 0xd6b0000
	v_mov_b32_e32 v3, s4
	global_atomic_add v2, v2, v3, s[68:69] offset:1024 sc0

; __device__ __forceinline__ unsigned xb_ld(unsigned* p)              { return __hip_atomic_load(p, __ATOMIC_RELAXED, __HIP_MEMORY_SCOPE_AGENT); }
; __device__ __forceinline__ unsigned xb_add(unsigned* p, unsigned v) { return __hip_atomic_fetch_add(p, v, __ATOMIC_RELAXED, __HIP_MEMORY_SCOPE_AGENT); }
; #define XB_SPIN(cond, bar) do { unsigned _sp = 0; while (cond) { __builtin_amdgcn_s_sleep(1); \
;     if ((++_sp & 255u) == 0u) { if (xb_ld(&(bar)[XB_TMO])) break; if (_sp > XB_SPIN_CAP) { atomicAdd(&(bar)[XB_TMO], 1u); break; } } } } while (0)
; __device__ __forceinline__ void xcd_barrier(const XcdBarrier& b) {
;     ...
;             else XB_SPIN(xb_ld(&bar[XB_TOPGEN]) == tg, bar);
;             __builtin_amdgcn_fence(__ATOMIC_ACQUIRE, "agent");
;             xb_add(&bar[XB_XGEN(b.x)], 1u);
;             asm volatile("s_waitcnt vmcnt(0)" ::: "memory");
.LBB0_123:
	s_or_b64 exec, exec, s[4:5]
	s_mov_b64 s[4:5], exec
	v_mbcnt_lo_u32_b32 v0, s4, 0
	v_mbcnt_hi_u32_b32 v0, s5, v0
	v_cmp_eq_u32_e32 vcc, 0, v0
	s_waitcnt vmcnt(0)
	s_and_saveexec_b64 s[6:7], vcc
	s_cbranch_execz .LBB0_125
	s_bcnt1_i32_b64 s4, s[4:5]
	v_mov_b32_e32 v0, 0x2000
	v_mov_b32_e32 v1, s4
